# PRI0: one static s_setprio 1 for waves 0-3 (older half) during the prompt attention tile loop, on the combined best
# baseline (speedup 1.0000x reference)
; __device__ __forceinline__ void attn_unit(const Args& a, LAS unsigned char* lds, const int mode, const int h, const int qb, const int tid_in, const int lane_in, const int wave) {
;     ...
;     float m_run = -INFINITY, l_run = 0.f, cqm = 0.f; f32x16 o0 = {}, o1 = {};
;     int jstart = 0;
;     if (mode == 0 && qb > 0) {
;         float dsc = 0.f;
; #pragma unroll
;         for (int d0 = 0; d0 < 4; ++d0) { const u32x4 kw = *(const u32x4*)(Kb + (size_t)qrow * D + h * HD + d0 * 16 + hi * 8); const u32x4 qw = __builtin_bit_cast(u32x4, qr[d0]);
;             const unsigned kk[4] = {kw.x, kw.y, kw.z, kw.w}; const unsigned qq[4] = {qw.x, qw.y, qw.z, qw.w};
; #pragma unroll
;             for (int e = 0; e < 4; ++e) dsc += __uint_as_float(kk[e] << 16) * __uint_as_float(qq[e] << 16) + __uint_as_float(kk[e] & 0xffff0000u) * __uint_as_float(qq[e] & 0xffff0000u); }
;         dsc += __shfl_xor(dsc, 32);
; #pragma unroll
;         for (int o = 1; o < 32; o <<= 1) dsc = fminf(dsc, __shfl_xor(dsc, o));
;         float qsq = 0.f;
; #pragma unroll
;         for (int d0 = 0; d0 < 4; ++d0) { const u32x4 qw = __builtin_bit_cast(u32x4, qr[d0]); const unsigned qq[4] = {qw.x, qw.y, qw.z, qw.w};
; #pragma unroll
;             for (int e = 0; e < 4; ++e) { const float lo = __uint_as_float(qq[e] << 16), hi_ = __uint_as_float(qq[e] & 0xffff0000u); qsq += lo * lo + hi_ * hi_; } }
;         qsq += __shfl_xor(qsq, 32);
; #pragma unroll
;         for (int o = 1; o < 32; o <<= 1) qsq = fmaxf(qsq, __shfl_xor(qsq, o));
;         LAS float* red = (LAS float*)(lds + AT_END);
;         if (lane == 0) { red[wave] = dsc; red[8 + wave] = qsq; }
;         __syncthreads();
;         float dmin = red[0], qn = red[8];
; #pragma unroll
;         for (int w = 1; w < 8; ++w) { dmin = fminf(dmin, red[w]); qn = fmaxf(qn, red[8 + w]); }
;         const float* N2 = (const float*)(ws + WS_N2); const float* PF = (const float*)(ws + WS_PFXP) + h * 256;
;         const float cq0 = (PF[qb * 4] + CLT[qb * 256]) * L2E, base = cq0 - dmin + 0.05f + 30.f;
;         int cnt = 0; bool open = true;
; #pragma unroll
;         for (int i = 0; i < 4; ++i) { const int j = lane + 64 * i; bool sk = false;
;             if (j < 4 * qb) sk = (base - PF[j + 1] * L2E + sqrtf(qn * N2[j * 32 + 16 + h]) * 1.01f) < 0.f;
;             const unsigned long long m = __ballot(sk); const bool full = (m == ~0ull);
.LBB0_516:
	s_or_b64 exec, exec, s[0:1]
	v_mul_lo_u32 v5, v2, s25
	v_lshlrev_b32_e32 v4, 4, v4
	v_add3_u32 v91, 0, v5, v4
	v_lshl_add_u32 v95, v2, 4, v91
	v_lshl_add_u32 v96, v1, 2, 0
	s_waitcnt vmcnt(1)
	ds_write_b128 v91, v[82:85]
	s_waitcnt vmcnt(0)
	ds_write_b128 v95, v[86:89] offset:18432
	s_and_saveexec_b64 s[0:1], s[2:3]
	ds_write_b32 v96, v97 offset:38912
	s_or_b64 exec, exec, s[0:1]
	s_add_i32 s16, s16, 4
	s_cmp_ge_i32 s12, s16
	s_waitcnt lgkmcnt(0)
	s_barrier
	s_cbranch_scc1 .LBB0_539
	v_add_f32_e32 v4, v9, v10
	v_or_b32_e32 v94, s14, v3
	v_lshlrev_b32_e32 v102, 2, v7
	v_lshrrev_b32_e32 v3, 2, v1
	v_mul_f32_e32 v100, 0x3fb8aa3b, v4
	v_and_or_b32 v3, v3, 3, v102
	s_movk_i32 s0, 0xa0
	v_lshlrev_b32_e32 v4, 1, v8
	v_lshlrev_b32_e32 v5, 3, v8
	v_lshl_add_u32 v98, v7, 4, 0
	v_mad_u32_u24 v3, v3, s0, 0
	v_and_b32_e32 v4, 32, v4
	v_and_b32_e32 v5, 24, v5
	v_mov_b32_e32 v14, v0
	v_mov_b32_e32 v15, v0
	v_sub_u32_e32 v99, v92, v6
	v_add3_u32 v104, v3, v4, v5
	v_mad_u32_u24 v105, v6, s25, v98
	v_add_u32_e32 v106, 64, v1
	v_add_u32_e32 v107, 64, v2
	v_mov_b32_e32 v1, v0
	v_mov_b32_e32 v2, v0
	v_mov_b32_e32 v3, v0
	v_mov_b32_e32 v4, v0
	v_mov_b32_e32 v5, v0
	v_mov_b32_e32 v6, v0
	v_mov_b32_e32 v7, v0
	v_mov_b32_e32 v8, v0
	v_mov_b32_e32 v9, v0
	v_mov_b32_e32 v10, v0
	v_mov_b32_e32 v11, v0
	v_mov_b32_e32 v12, v0
	v_mov_b32_e32 v13, v0
	v_mov_b64_e32 v[32:33], v[14:15]
	s_add_i32 s15, s12, s15
	v_mov_b64_e32 v[30:31], v[12:13]
	v_mov_b64_e32 v[28:29], v[10:11]
	v_mov_b64_e32 v[26:27], v[8:9]
	v_mov_b64_e32 v[24:25], v[6:7]
	v_mov_b64_e32 v[22:23], v[4:5]
	v_mov_b64_e32 v[20:21], v[2:3]
	v_mov_b64_e32 v[18:19], v[0:1]
	v_mov_b64_e32 v[16:17], v[14:15]
	v_add_u32_e32 v101, 31, v99
	s_add_i32 s15, s15, 1
	s_mov_b32 s17, 0
	v_mov_b32_e32 v108, 0xff800000
	v_mov_b32_e32 v103, 0
	v_mov_b64_e32 v[14:15], v[12:13]
	v_mov_b64_e32 v[12:13], v[10:11]
	v_mov_b64_e32 v[10:11], v[8:9]
	v_mov_b64_e32 v[8:9], v[6:7]
	v_mov_b64_e32 v[6:7], v[4:5]
	v_mov_b64_e32 v[4:5], v[2:3]
	v_mov_b64_e32 v[2:3], v[0:1]
	v_mov_b32_e32 v1, 0
	v_readlane_b32 s100, v254, 21
	s_nop 3
	s_lshr_b32 s100, s100, 2
	s_cmp_eq_u32 s100, 0
	s_cbranch_scc0 .Lpa_noprio
	s_setprio 1
